# seams: the first workgroup to arrive on its XCD also starts an early L2 write-back (in addition to the second-to-last)
# baseline (speedup 1.0000x reference)
; __device__ __forceinline__ unsigned xb_ld(unsigned* p)              { return __hip_atomic_load(p, __ATOMIC_RELAXED, __HIP_MEMORY_SCOPE_AGENT); }
; __device__ __forceinline__ unsigned xb_add(unsigned* p, unsigned v) { return __hip_atomic_fetch_add(p, v, __ATOMIC_RELAXED, __HIP_MEMORY_SCOPE_AGENT); }
; #define XB_SPIN(cond, bar) do { unsigned _sp = 0; while (cond) { __builtin_amdgcn_s_sleep(1); \
;     if ((++_sp & 255u) == 0u) { if (xb_ld(&(bar)[XB_TMO])) break; if (_sp > XB_SPIN_CAP) { atomicAdd(&(bar)[XB_TMO], 1u); break; } } } } while (0)
; __device__ __forceinline__ void xcd_barrier(const XcdBarrier& b, const int wv) {
;     ...
;         unsigned nloc = b.st[0], nx = b.st[1];
;         if (nloc == 0u) { xcd_barrier_complete(bar, b.x, nloc, nx); b.st[0] = nloc; b.st[1] = nx; }
;         const unsigned old = xb_add(&bar[XB_XSUB(b.x)], 1u);
;         const unsigned gen = old / nloc;
;         if (old + 1u == (gen + 1u) * nloc) {
;             __builtin_amdgcn_fence(__ATOMIC_RELEASE, "agent");
;             asm volatile("s_waitcnt vmcnt(0)" ::: "memory");
;             const unsigned og = xb_add(&bar[XB_TOP], 1u);
;             const unsigned tg = og / nx;
;             if (og + 1u == (tg + 1u) * nx) xb_add(&bar[XB_TOPGEN], 1u);
;             else XB_SPIN(xb_ld(&bar[XB_TOPGEN]) == tg, bar);
.Lseam1_328:
	s_or_b64 exec, exec, s[14:15]
	v_cvt_f32_u32_e32 v4, v2
	s_waitcnt vmcnt(0)
	v_readfirstlane_b32 s3, v3
	v_sub_u32_e32 v3, 0, v2
	v_rcp_iflag_f32_e32 v4, v4
	v_add_u32_e32 v5, s3, v1
	v_mul_f32_e32 v4, 0x4f7ffffe, v4
	v_cvt_u32_f32_e32 v4, v4
	v_mul_lo_u32 v1, v3, v4
	v_mul_hi_u32 v1, v4, v1
	v_add_u32_e32 v1, v4, v1
	v_mul_hi_u32 v1, v5, v1
	v_mul_lo_u32 v3, v1, v2
	v_sub_u32_e32 v3, v5, v3
	v_add_u32_e32 v4, 1, v1
	v_cmp_ge_u32_e32 vcc, v3, v2
	s_nop 1
	v_cndmask_b32_e32 v1, v1, v4, vcc
	v_sub_u32_e32 v4, v3, v2
	v_cndmask_b32_e32 v3, v3, v4, vcc
	v_add_u32_e32 v4, 1, v1
	v_cmp_ge_u32_e32 vcc, v3, v2
	v_add_u32_e32 v3, 1, v5
	s_nop 0
	v_cndmask_b32_e32 v1, v1, v4, vcc
	v_mul_lo_u32 v4, v2, v1
	v_add_u32_e32 v2, v4, v2
	v_cmp_ne_u32_e32 vcc, v3, v2
	s_and_saveexec_b64 s[12:13], vcc
	s_xor_b64 s[12:13], exec, s[12:13]
	s_cbranch_execz .Lseam1_342
	v_add_u32_e32 v19, 1, v3
	v_cmp_eq_u32_e32 vcc, v19, v2
	s_cbranch_vccnz .Lpf4_0
	v_add_u32_e32 v19, 1, v4
	v_cmp_eq_u32_e32 vcc, v19, v3
	s_cbranch_vccz .Lpf2_0

; __device__ __forceinline__ unsigned xb_ld(unsigned* p)              { return __hip_atomic_load(p, __ATOMIC_RELAXED, __HIP_MEMORY_SCOPE_AGENT); }
; __device__ __forceinline__ unsigned xb_add(unsigned* p, unsigned v) { return __hip_atomic_fetch_add(p, v, __ATOMIC_RELAXED, __HIP_MEMORY_SCOPE_AGENT); }
; #define XB_SPIN(cond, bar) do { unsigned _sp = 0; while (cond) { __builtin_amdgcn_s_sleep(1); \
;     if ((++_sp & 255u) == 0u) { if (xb_ld(&(bar)[XB_TMO])) break; if (_sp > XB_SPIN_CAP) { atomicAdd(&(bar)[XB_TMO], 1u); break; } } } } while (0)
; __device__ __forceinline__ void xcd_barrier(const XcdBarrier& b, const int wv) {
;     ...
;         unsigned nloc = b.st[0], nx = b.st[1];
;         if (nloc == 0u) { xcd_barrier_complete(bar, b.x, nloc, nx); b.st[0] = nloc; b.st[1] = nx; }
;         const unsigned old = xb_add(&bar[XB_XSUB(b.x)], 1u);
;         const unsigned gen = old / nloc;
;         if (old + 1u == (gen + 1u) * nloc) {
;             __builtin_amdgcn_fence(__ATOMIC_RELEASE, "agent");
;             asm volatile("s_waitcnt vmcnt(0)" ::: "memory");
;             const unsigned og = xb_add(&bar[XB_TOP], 1u);
;             const unsigned tg = og / nx;
;             if (og + 1u == (tg + 1u) * nx) xb_add(&bar[XB_TOPGEN], 1u);
;             else XB_SPIN(xb_ld(&bar[XB_TOPGEN]) == tg, bar);
.LBB0_727:
	s_or_b64 exec, exec, s[16:17]
	v_cvt_f32_u32_e32 v4, v2
	s_waitcnt vmcnt(0)
	v_readfirstlane_b32 s3, v3
	v_sub_u32_e32 v3, 0, v2
	v_rcp_iflag_f32_e32 v4, v4
	v_add_u32_e32 v5, s3, v1
	v_mul_f32_e32 v4, 0x4f7ffffe, v4
	v_cvt_u32_f32_e32 v4, v4
	v_mul_lo_u32 v1, v3, v4
	v_mul_hi_u32 v1, v4, v1
	v_add_u32_e32 v1, v4, v1
	v_mul_hi_u32 v1, v5, v1
	v_mul_lo_u32 v3, v1, v2
	v_sub_u32_e32 v3, v5, v3
	v_add_u32_e32 v4, 1, v1
	v_cmp_ge_u32_e32 vcc, v3, v2
	s_nop 1
	v_cndmask_b32_e32 v1, v1, v4, vcc
	v_sub_u32_e32 v4, v3, v2
	v_cndmask_b32_e32 v3, v3, v4, vcc
	v_add_u32_e32 v4, 1, v1
	v_cmp_ge_u32_e32 vcc, v3, v2
	v_add_u32_e32 v3, 1, v5
	s_nop 0
	v_cndmask_b32_e32 v1, v1, v4, vcc
	v_mul_lo_u32 v4, v2, v1
	v_add_u32_e32 v2, v4, v2
	v_cmp_ne_u32_e32 vcc, v3, v2
	s_and_saveexec_b64 s[14:15], vcc
	s_xor_b64 s[14:15], exec, s[14:15]
	s_cbranch_execz .LBB0_741
	v_add_u32_e32 v19, 1, v3
	v_cmp_eq_u32_e32 vcc, v19, v2
	s_cbranch_vccnz .Lpf4_4
	v_add_u32_e32 v19, 1, v4
	v_cmp_eq_u32_e32 vcc, v19, v3
	s_cbranch_vccz .Lpf2_4

; __device__ __forceinline__ unsigned xb_ld(unsigned* p)              { return __hip_atomic_load(p, __ATOMIC_RELAXED, __HIP_MEMORY_SCOPE_AGENT); }
; __device__ __forceinline__ unsigned xb_add(unsigned* p, unsigned v) { return __hip_atomic_fetch_add(p, v, __ATOMIC_RELAXED, __HIP_MEMORY_SCOPE_AGENT); }
; #define XB_SPIN(cond, bar) do { unsigned _sp = 0; while (cond) { __builtin_amdgcn_s_sleep(1); \
;     if ((++_sp & 255u) == 0u) { if (xb_ld(&(bar)[XB_TMO])) break; if (_sp > XB_SPIN_CAP) { atomicAdd(&(bar)[XB_TMO], 1u); break; } } } } while (0)
; __device__ __forceinline__ void xcd_barrier(const XcdBarrier& b, const int wv) {
;     ...
;         unsigned nloc = b.st[0], nx = b.st[1];
;         if (nloc == 0u) { xcd_barrier_complete(bar, b.x, nloc, nx); b.st[0] = nloc; b.st[1] = nx; }
;         const unsigned old = xb_add(&bar[XB_XSUB(b.x)], 1u);
;         const unsigned gen = old / nloc;
;         if (old + 1u == (gen + 1u) * nloc) {
;             __builtin_amdgcn_fence(__ATOMIC_RELEASE, "agent");
;             asm volatile("s_waitcnt vmcnt(0)" ::: "memory");
;             const unsigned og = xb_add(&bar[XB_TOP], 1u);
;             const unsigned tg = og / nx;
;             if (og + 1u == (tg + 1u) * nx) xb_add(&bar[XB_TOPGEN], 1u);
;             else XB_SPIN(xb_ld(&bar[XB_TOPGEN]) == tg, bar);
.LBB0_860:
	s_or_b64 exec, exec, s[18:19]
	v_cvt_f32_u32_e32 v4, v2
	s_waitcnt vmcnt(0)
	v_readfirstlane_b32 s3, v3
	v_sub_u32_e32 v3, 0, v2
	v_rcp_iflag_f32_e32 v4, v4
	v_add_u32_e32 v5, s3, v1
	v_mul_f32_e32 v4, 0x4f7ffffe, v4
	v_cvt_u32_f32_e32 v4, v4
	v_mul_lo_u32 v1, v3, v4
	v_mul_hi_u32 v1, v4, v1
	v_add_u32_e32 v1, v4, v1
	v_mul_hi_u32 v1, v5, v1
	v_mul_lo_u32 v3, v1, v2
	v_sub_u32_e32 v3, v5, v3
	v_add_u32_e32 v4, 1, v1
	v_cmp_ge_u32_e32 vcc, v3, v2
	s_nop 1
	v_cndmask_b32_e32 v1, v1, v4, vcc
	v_sub_u32_e32 v4, v3, v2
	v_cndmask_b32_e32 v3, v3, v4, vcc
	v_add_u32_e32 v4, 1, v1
	v_cmp_ge_u32_e32 vcc, v3, v2
	v_add_u32_e32 v3, 1, v5
	s_nop 0
	v_cndmask_b32_e32 v1, v1, v4, vcc
	v_mul_lo_u32 v4, v2, v1
	v_add_u32_e32 v2, v4, v2
	v_cmp_ne_u32_e32 vcc, v3, v2
	s_and_saveexec_b64 s[16:17], vcc
	s_xor_b64 s[16:17], exec, s[16:17]
	s_cbranch_execz .LBB0_874
	v_add_u32_e32 v19, 1, v3
	v_cmp_eq_u32_e32 vcc, v19, v2
	s_cbranch_vccnz .Lpf4_6
	v_add_u32_e32 v19, 1, v4
	v_cmp_eq_u32_e32 vcc, v19, v3
	s_cbranch_vccz .Lpf2_6
